# stick-breaking block: fold the min(score,80) clamp into the copy out of the QK accumulator (32 v_min removed per half-tile pair)
# baseline (speedup 1.0000x reference)
.LBB0_461:
	s_add_i32 s12, s73, s15
	v_add_u32_e32 v38, s12, v98
	v_add_u32_e32 v34, v38, v101
	ds_read_b128 v[34:37], v34
	v_add_u32_e32 v39, v38, v102
	ds_read_b128 v[86:89], v39
	v_add_u32_e32 v39, v38, v103
	v_add_u32_e32 v38, v38, v104
	ds_read_b128 v[114:117], v38
	v_add3_u32 v38, s12, v99, v100
	ds_read_b128 v[110:113], v39
	v_add3_u32 v39, v38, v106, v105
	v_add3_u32 v38, v38, v107, v105
	ds_read_b64_tr_b16 v[78:79], v39 offset:4096
	ds_read_b64_tr_b16 v[80:81], v39 offset:5120
	ds_read_b64_tr_b16 v[70:71], v39 offset:6144
	ds_read_b64_tr_b16 v[72:73], v39 offset:7168
	ds_read_b64_tr_b16 v[74:75], v38 offset:4096
	ds_read_b64_tr_b16 v[76:77], v38 offset:5120
	ds_read_b64_tr_b16 v[66:67], v38 offset:6144
	ds_read_b64_tr_b16 v[68:69], v38 offset:7168
	s_waitcnt lgkmcnt(11)
	v_mfma_f32_32x32x16_bf16 v[34:49], v[34:37], v[50:53], 0
	s_or_b32 s15, s14, 31
	s_mov_b64 s[12:13], -1
	s_cmp_ge_i32 s15, s85
	s_waitcnt lgkmcnt(10)
	v_mfma_f32_32x32x16_bf16 v[34:49], v[86:89], v[54:57], v[34:49]
	s_waitcnt lgkmcnt(8)
	v_mfma_f32_32x32x16_bf16 v[34:49], v[110:113], v[58:61], v[34:49]
	v_mfma_f32_32x32x16_bf16 v[34:49], v[114:117], v[62:65], v[34:49]
	s_nop 11
	v_min_f32_e32 v117, 0x42a00000, v34
	v_min_f32_e32 v116, 0x42a00000, v35
	v_min_f32_e32 v115, 0x42a00000, v36
	v_min_f32_e32 v114, 0x42a00000, v37
	v_min_f32_e32 v89, 0x42a00000, v38
	v_min_f32_e32 v88, 0x42a00000, v39
	v_min_f32_e32 v86, 0x42a00000, v40
	v_min_f32_e32 v87, 0x42a00000, v41
	v_min_f32_e32 v90, 0x42a00000, v42
	v_min_f32_e32 v91, 0x42a00000, v43
	v_min_f32_e32 v113, 0x42a00000, v44
	v_min_f32_e32 v112, 0x42a00000, v45
	v_min_f32_e32 v111, 0x42a00000, v46
	v_min_f32_e32 v110, 0x42a00000, v47
	v_min_f32_e32 v109, 0x42a00000, v48
	v_min_f32_e32 v85, 0x42a00000, v49
	s_cbranch_scc0 .LBB0_463
	v_or_b32_e32 v35, s14, v97
	v_or_b32_e32 v37, 1, v35
	v_cmp_lt_i32_e64 s[12:13], v37, v82
	v_exp_f32_e32 v120, v115
	v_or_b32_e32 v38, 2, v35
	v_cmp_lt_i32_e64 s[14:15], v38, v82
	v_or_b32_e32 v39, 3, v35
	v_add_f32_e32 v37, 1.0, v120
	v_rcp_f32_e32 v37, v37
	v_cmp_lt_i32_e64 s[16:17], v39, v82
	v_or_b32_e32 v39, 8, v35
	v_cmp_lt_i32_e64 s[18:19], v39, v82
	v_cndmask_b32_e64 v38, 1.0, v37, s[14:15]
	v_exp_f32_e32 v121, v114
	v_or_b32_e32 v39, 9, v35
	v_cmp_lt_i32_e64 s[20:21], v39, v82
	v_or_b32_e32 v39, 10, v35
	v_add_f32_e32 v37, 1.0, v121
	v_rcp_f32_e32 v37, v37
	v_cmp_lt_i32_e64 s[22:23], v39, v82
	v_or_b32_e32 v39, 11, v35
	v_cmp_lt_i32_e64 s[24:25], v39, v82
	v_cndmask_b32_e64 v40, 1.0, v37, s[16:17]
	v_exp_f32_e32 v130, v89
	v_or_b32_e32 v39, 16, v35
	v_cmp_lt_i32_e64 s[26:27], v39, v82
	v_or_b32_e32 v39, 17, v35
	v_add_f32_e32 v37, 1.0, v130
	v_rcp_f32_e32 v37, v37
	v_cmp_lt_i32_e64 s[28:29], v39, v82
	v_or_b32_e32 v39, 18, v35
	v_cmp_lt_i32_e64 s[30:31], v39, v82
	v_cndmask_b32_e64 v42, 1.0, v37, s[18:19]
	v_exp_f32_e32 v131, v88
	v_or_b32_e32 v39, 19, v35
	v_cmp_lt_i32_e64 s[34:35], v39, v82
	v_or_b32_e32 v39, 24, v35
	v_add_f32_e32 v37, 1.0, v131
	v_rcp_f32_e32 v37, v37
	v_cmp_lt_i32_e64 s[36:37], v39, v82
	v_or_b32_e32 v39, 25, v35
	v_cmp_lt_i32_e64 s[38:39], v39, v82
	v_cndmask_b32_e64 v44, 1.0, v37, s[20:21]
	v_exp_f32_e32 v132, v86
	v_or_b32_e32 v39, 26, v35
	v_cmp_lt_i32_e64 s[40:41], v39, v82
	v_cmp_lt_i32_e32 vcc, v35, v82
	v_add_f32_e32 v37, 1.0, v132
	v_rcp_f32_e32 v37, v37
	v_or_b32_e32 v35, 27, v35
	v_cmp_lt_i32_e64 s[42:43], v35, v82
	v_xor_b32_e32 v35, 32, v238
	v_cndmask_b32_e64 v45, 1.0, v37, s[22:23]
	v_exp_f32_e32 v133, v87
	v_exp_f32_e32 v118, v117
	v_add_f32_e32 v37, 1.0, v133
	v_rcp_f32_e32 v37, v37
	v_exp_f32_e32 v119, v116
	v_add_f32_e32 v34, 1.0, v118
	v_rcp_f32_e32 v34, v34
	v_cndmask_b32_e64 v43, 1.0, v37, s[24:25]
	v_exp_f32_e32 v134, v90
	v_pk_mul_f32 v[126:127], v[44:45], v[42:43]
	v_add_f32_e32 v36, 1.0, v119
	v_pk_mul_f32 v[126:127], v[126:127], v[126:127] op_sel:[0,1] op_sel_hi:[1,0]
	v_add_f32_e32 v37, 1.0, v134
	v_rcp_f32_e32 v37, v37
	v_rcp_f32_e32 v36, v36
	v_cndmask_b32_e32 v34, 1.0, v34, vcc
	v_cndmask_b32_e32 v118, 0, v118, vcc
	v_cndmask_b32_e64 v46, 1.0, v37, s[26:27]
	v_exp_f32_e32 v135, v91
	v_cndmask_b32_e64 v36, 1.0, v36, s[12:13]
	v_cndmask_b32_e64 v119, 0, v119, s[12:13]
	v_cndmask_b32_e64 v120, 0, v120, s[14:15]
	v_add_f32_e32 v37, 1.0, v135
	v_rcp_f32_e32 v37, v37
	v_cndmask_b32_e64 v121, 0, v121, s[16:17]
	s_mov_b64 s[12:13], 0
	v_cndmask_b32_e64 v48, 1.0, v37, s[28:29]
	v_exp_f32_e32 v136, v113
	s_nop 0
	v_add_f32_e32 v37, 1.0, v136
	v_rcp_f32_e32 v37, v37
	s_nop 0
	v_cndmask_b32_e64 v49, 1.0, v37, s[30:31]
	v_exp_f32_e32 v137, v112
	s_nop 0
	v_add_f32_e32 v37, 1.0, v137
	v_rcp_f32_e32 v37, v37
	s_nop 0
	v_cndmask_b32_e64 v47, 1.0, v37, s[34:35]
	v_exp_f32_e32 v138, v111
	v_pk_mul_f32 v[128:129], v[48:49], v[46:47]
	v_add_f32_e32 v37, 1.0, v138
	v_rcp_f32_e32 v37, v37
	s_nop 0
	v_cndmask_b32_e64 v122, 1.0, v37, s[36:37]
	v_exp_f32_e32 v139, v110
	s_nop 0
	v_add_f32_e32 v37, 1.0, v139
	v_rcp_f32_e32 v37, v37
	s_nop 0
	v_cndmask_b32_e64 v124, 1.0, v37, s[38:39]
	v_exp_f32_e32 v140, v109
	s_nop 0
	v_add_f32_e32 v37, 1.0, v140
	v_rcp_f32_e32 v37, v37
	s_nop 0
	v_cndmask_b32_e64 v125, 1.0, v37, s[40:41]
	v_exp_f32_e32 v141, v85
	s_nop 0
	v_add_f32_e32 v37, 1.0, v141
	v_rcp_f32_e32 v37, v37
	s_nop 0
	v_cndmask_b32_e64 v123, 1.0, v37, s[42:43]
	v_and_b32_e32 v37, 64, v238
	v_add_u32_e32 v37, 64, v37
	v_cmp_lt_i32_e64 s[44:45], v35, v37
	s_nop 1
	v_cndmask_b32_e64 v35, v238, v35, s[44:45]
	v_lshlrev_b32_e32 v142, 2, v35
	v_mul_f32_e32 v35, v128, v129
	v_pk_mul_f32 v[128:129], v[124:125], v[122:123]
	ds_bpermute_b32 v39, v142, v35
	v_mul_f32_e32 v41, v128, v129
	ds_bpermute_b32 v127, v142, v41
	ds_bpermute_b32 v37, v142, v126
	s_waitcnt lgkmcnt(1)
	v_mul_f32_e32 v41, v41, v127
	v_mul_f32_e32 v41, v108, v41
	v_mul_f32_e32 v128, v108, v127
	v_mul_f32_e32 v127, v41, v39
	v_mul_f32_e32 v39, v35, v39
	v_mov_b32_e32 v35, v126
	v_cndmask_b32_e64 v143, v108, v128, s[10:11]
	v_cndmask_b32_e64 v144, v41, v127, s[10:11]
	v_pk_mul_f32 v[128:129], v[38:39], v[40:41]
	s_waitcnt lgkmcnt(0)
	v_pk_mul_f32 v[126:127], v[34:35], v[36:37]
	v_mul_f32_e32 v35, v129, v37
	v_pk_mul_f32 v[126:127], v[126:127], v[128:129]
	ds_bpermute_b32 v145, v142, v126
	v_cndmask_b32_e64 v35, v129, v35, s[10:11]
	v_cndmask_b32_e64 v129, 0, v131, s[20:21]
	v_cndmask_b32_e64 v131, 0, v133, s[24:25]
	v_cndmask_b32_e64 v133, 0, v135, s[28:29]
	s_waitcnt lgkmcnt(0)
	v_mul_f32_e32 v37, v127, v145
	v_cndmask_b32_e64 v135, 0, v137, s[34:35]
	v_cndmask_b32_e64 v137, 0, v139, s[38:39]
	v_cndmask_b32_e64 v139, 0, v141, s[42:43]
	v_mul_f32_e32 v141, v123, v143
	v_cndmask_b32_e64 v37, v127, v37, s[10:11]
	v_cndmask_b32_e64 v128, 0, v130, s[18:19]
	v_cndmask_b32_e64 v130, 0, v132, s[22:23]
	v_cndmask_b32_e64 v132, 0, v134, s[26:27]
	v_cndmask_b32_e64 v134, 0, v136, s[30:31]
	v_cndmask_b32_e64 v136, 0, v138, s[36:37]
	v_cndmask_b32_e64 v138, 0, v140, s[40:41]
	v_mul_f32_e32 v140, v125, v141
	v_mul_f32_e32 v125, v47, v144
	v_mul_f32_e32 v123, v124, v140
	v_mul_f32_e32 v124, v49, v125
	v_mul_f32_e32 v39, v40, v37
	v_mul_f32_e32 v143, v48, v124
	v_mul_f32_e32 v47, v43, v35
	v_mul_f32_e32 v38, v38, v39
	v_mul_f32_e32 v142, v46, v143
	v_mul_f32_e32 v46, v45, v47
	v_mul_f32_e32 v35, v36, v38
	v_mul_f32_e32 v43, v44, v46
	v_mul_f32_e32 v34, v34, v35
	v_mul_f32_e32 v122, v122, v123
	v_mul_f32_e32 v42, v42, v43
	v_pk_mul_f32 v[48:49], v[118:119], v[34:35]
	v_mul_f32_e32 v118, v126, v145
	v_pk_mul_f32 v[40:41], v[130:131], v[46:47]
	v_pk_mul_f32 v[44:45], v[128:129], v[42:43]
	v_pk_mul_f32 v[46:47], v[120:121], v[38:39]
	v_pk_mul_f32 v[34:35], v[134:135], v[124:125]
	v_pk_mul_f32 v[38:39], v[132:133], v[142:143]
	v_pk_mul_f32 v[36:37], v[138:139], v[140:141]
	v_pk_mul_f32 v[42:43], v[136:137], v[122:123]
	v_mul_f32_e32 v118, v118, v127
.LBB0_463:
	s_andn2_b64 vcc, exec, s[12:13]
	s_cbranch_vccnz .LBB0_465
	v_exp_f32_e32 v34, v117
	v_and_b32_e32 v39, 64, v238
	v_add_u32_e32 v39, 64, v39
	v_add_f32_e32 v35, 1.0, v34
	v_rcp_f32_e32 v36, v35
	v_exp_f32_e32 v35, v116
	s_nop 0
	v_add_f32_e32 v37, 1.0, v35
	v_rcp_f32_e32 v38, v37
	v_exp_f32_e32 v40, v115
	s_nop 0
	v_add_f32_e32 v37, 1.0, v40
	v_rcp_f32_e32 v42, v37
	v_exp_f32_e32 v41, v114
	s_nop 0
	v_add_f32_e32 v37, 1.0, v41
	v_rcp_f32_e32 v46, v37
	v_exp_f32_e32 v44, v89
	s_nop 0
	v_add_f32_e32 v37, 1.0, v44
	v_rcp_f32_e32 v48, v37
	v_exp_f32_e32 v45, v88
	s_nop 0
	v_add_f32_e32 v37, 1.0, v45
	v_rcp_f32_e32 v88, v37
	v_exp_f32_e32 v86, v86
	s_nop 0
	v_add_f32_e32 v37, 1.0, v86
	v_rcp_f32_e32 v49, v37
	v_exp_f32_e32 v87, v87
	s_nop 0
	v_add_f32_e32 v37, 1.0, v87
	v_rcp_f32_e32 v89, v37
	v_exp_f32_e32 v90, v90
	v_pk_mul_f32 v[124:125], v[48:49], v[88:89]
	s_nop 0
	v_pk_mul_f32 v[124:125], v[124:125], v[124:125] op_sel:[0,1] op_sel_hi:[1,0]
	v_add_f32_e32 v37, 1.0, v90
	v_rcp_f32_e32 v114, v37
	v_exp_f32_e32 v91, v91
	s_nop 0
	v_add_f32_e32 v37, 1.0, v91
	v_rcp_f32_e32 v116, v37
	v_exp_f32_e32 v118, v113
	s_nop 0
	v_add_f32_e32 v37, 1.0, v118
	v_rcp_f32_e32 v115, v37
	v_exp_f32_e32 v119, v112
	s_nop 0
	v_add_f32_e32 v37, 1.0, v119
	v_rcp_f32_e32 v117, v37
	v_exp_f32_e32 v112, v111
	v_pk_mul_f32 v[126:127], v[114:115], v[116:117]
	v_add_f32_e32 v37, 1.0, v112
	v_rcp_f32_e32 v120, v37
	v_exp_f32_e32 v113, v110
	s_nop 0
	v_add_f32_e32 v37, 1.0, v113
	v_rcp_f32_e32 v110, v37
	v_exp_f32_e32 v122, v109
	s_nop 0
	v_add_f32_e32 v37, 1.0, v122
	v_rcp_f32_e32 v121, v37
	v_exp_f32_e32 v123, v85
	s_nop 0
	v_add_f32_e32 v37, 1.0, v123
	v_rcp_f32_e32 v111, v37
	v_xor_b32_e32 v37, 32, v238
	v_cmp_lt_i32_e32 vcc, v37, v39
	s_nop 1
	v_cndmask_b32_e32 v37, v238, v37, vcc
	v_lshlrev_b32_e32 v85, 2, v37
	v_mul_f32_e32 v37, v126, v127
	v_pk_mul_f32 v[126:127], v[120:121], v[110:111]
	ds_bpermute_b32 v43, v85, v37
	v_mul_f32_e32 v47, v126, v127
	ds_bpermute_b32 v109, v85, v47
	ds_bpermute_b32 v39, v85, v124
	s_waitcnt lgkmcnt(1)
	v_mul_f32_e32 v47, v47, v109
	v_mul_f32_e32 v125, v108, v109
	v_mul_f32_e32 v47, v108, v47
	v_cndmask_b32_e64 v126, v108, v125, s[10:11]
	v_mul_f32_e32 v108, v47, v43
	v_mul_f32_e32 v43, v37, v43
	v_mov_b32_e32 v37, v124
	v_cndmask_b32_e64 v127, v47, v108, s[10:11]
	v_pk_mul_f32 v[108:109], v[42:43], v[46:47]
	s_waitcnt lgkmcnt(0)
	v_pk_mul_f32 v[124:125], v[36:37], v[38:39]
	v_mul_f32_e32 v37, v109, v39
	v_pk_mul_f32 v[124:125], v[124:125], v[108:109]
	ds_bpermute_b32 v85, v85, v124
	v_cndmask_b32_e64 v37, v109, v37, s[10:11]
	v_mul_f32_e32 v109, v111, v126
	v_mul_f32_e32 v108, v121, v109
	v_mul_f32_e32 v111, v110, v108
	s_waitcnt lgkmcnt(0)
	v_mul_f32_e32 v39, v125, v85
	v_cndmask_b32_e64 v39, v125, v39, s[10:11]
	v_mul_f32_e32 v121, v117, v127
	v_mul_f32_e32 v110, v120, v111
	v_mul_f32_e32 v120, v115, v121
	v_mul_f32_e32 v117, v89, v37
	v_mul_f32_e32 v43, v46, v39
	v_mul_f32_e32 v115, v116, v120
	v_mul_f32_e32 v116, v49, v117
	v_mul_f32_e32 v42, v42, v43
	v_mul_f32_e32 v89, v88, v116
	v_mul_f32_e32 v37, v38, v42
	v_mul_f32_e32 v114, v114, v115
	v_mul_f32_e32 v88, v48, v89
	v_mul_f32_e32 v36, v36, v37
	v_mul_f32_e32 v85, v124, v85
	v_pk_mul_f32 v[48:49], v[34:35], v[36:37]
	v_pk_mul_f32 v[46:47], v[40:41], v[42:43]
	v_pk_mul_f32 v[44:45], v[44:45], v[88:89]
	v_pk_mul_f32 v[40:41], v[86:87], v[116:117]
	v_pk_mul_f32 v[38:39], v[90:91], v[114:115]
	v_pk_mul_f32 v[34:35], v[118:119], v[120:121]
	v_pk_mul_f32 v[42:43], v[112:113], v[110:111]
	v_pk_mul_f32 v[36:37], v[122:123], v[108:109]
	v_mul_f32_e32 v118, v85, v125
